# grid barrier: the agent-scope invalidate is issued before the arrival atomic (overlaps its round trip) instead of after it; on top of all-to-all release
# speedup vs baseline: 1.0079x; 1.0021x over previous
.LBB0_167:
	v_readlane_b32 s0, v251, 23
	s_lshl_b32 s0, s0, 2
	s_add_u32 s21, s34, s0
	s_addc_u32 s20, s35, 0
	v_mov_b32_e32 v1, s21
	v_add_co_u32_e32 v6, vcc, 0x1000, v1
	v_mov_b32_e32 v1, s20
	s_nop 0
	v_addc_co_u32_e32 v7, vcc, 0, v1, vcc
	v_mov_b32_e32 v1, 1
	buffer_inv sc1
	flat_atomic_add v1, v[6:7], v1 offset:1024 sc0
	v_cvt_f32_u32_e32 v3, v4
	v_sub_u32_e32 v5, 0, v4
	v_readlane_b32 s1, v251, 24
	v_rcp_iflag_f32_e32 v3, v3
	s_nop 0
	v_mul_f32_e32 v3, 0x4f7ffffe, v3
	v_cvt_u32_f32_e32 v3, v3
	v_mul_lo_u32 v5, v5, v3
	v_mul_hi_u32 v5, v3, v5
	v_add_u32_e32 v3, v3, v5
	s_waitcnt vmcnt(0) lgkmcnt(0)
	v_mul_hi_u32 v3, v1, v3
	v_mul_lo_u32 v5, v3, v4
	v_add_u32_e32 v6, 1, v1
	v_sub_u32_e32 v1, v1, v5
	v_add_u32_e32 v7, 1, v3
	v_cmp_ge_u32_e32 vcc, v1, v4
	v_sub_u32_e32 v5, v1, v4
	s_nop 0
	v_cndmask_b32_e32 v3, v3, v7, vcc
	v_cndmask_b32_e32 v1, v1, v5, vcc
	v_add_u32_e32 v5, 1, v3
	v_cmp_ge_u32_e32 vcc, v1, v4
	s_nop 1
	v_cndmask_b32_e32 v1, v3, v5, vcc
	v_mad_u64_u32 v[4:5], s[0:1], v4, v1, v[4:5]
	v_cmp_ne_u32_e32 vcc, v6, v4
	s_and_saveexec_b64 s[0:1], vcc
	s_xor_b64 s[0:1], exec, s[0:1]
	s_cbranch_execz .LBB0_180
	v_mov_b32_e32 v2, s21
	v_add_co_u32_e32 v2, vcc, 0x2000, v2
	v_mov_b32_e32 v3, s20
	s_nop 0
	v_addc_co_u32_e32 v3, vcc, 0, v3, vcc
	flat_load_dword v2, v[2:3] offset:1024 sc1
	s_add_u32 s4, s21, 0x2400
	s_addc_u32 s5, s20, 0
	s_waitcnt vmcnt(0) lgkmcnt(0)
	v_cmp_eq_u32_e32 vcc, v2, v1
	s_and_saveexec_b64 s[2:3], vcc
	s_cbranch_execz .LBB0_179
	s_mov_b32 s22, 1
	s_mov_b64 s[6:7], 0
	s_branch .LBB0_171

.LBB0_247:
	v_readlane_b32 s4, v251, 23
	v_readlane_b32 s5, v251, 24
	s_lshl_b64 s[4:5], s[4:5], 2
	s_add_u32 s38, s2, s4
	s_addc_u32 s28, s3, s5
	v_mov_b32_e32 v3, s38
	v_add_co_u32_e32 v6, vcc, 0x1000, v3
	v_mov_b32_e32 v3, s28
	s_nop 0
	v_addc_co_u32_e32 v7, vcc, 0, v3, vcc
	buffer_inv sc1
	flat_atomic_add v5, v[6:7], v207 offset:1024 sc0
	v_cvt_f32_u32_e32 v3, v4
	v_sub_u32_e32 v6, 0, v4
	v_rcp_iflag_f32_e32 v3, v3
	s_nop 0
	v_mul_f32_e32 v3, 0x4f7ffffe, v3
	v_cvt_u32_f32_e32 v3, v3
	v_mul_lo_u32 v6, v6, v3
	v_mul_hi_u32 v6, v3, v6
	v_add_u32_e32 v3, v3, v6
	s_waitcnt vmcnt(0) lgkmcnt(0)
	v_mul_hi_u32 v3, v5, v3
	v_mul_lo_u32 v6, v3, v4
	v_sub_u32_e32 v6, v5, v6
	v_cmp_ge_u32_e32 vcc, v6, v4
	v_add_u32_e32 v7, 1, v3
	s_nop 0
	v_cndmask_b32_e32 v3, v3, v7, vcc
	v_sub_u32_e32 v7, v6, v4
	v_cndmask_b32_e32 v6, v6, v7, vcc
	v_cmp_ge_u32_e32 vcc, v6, v4
	v_add_u32_e32 v6, 1, v3
	s_nop 0
	v_cndmask_b32_e32 v3, v3, v6, vcc
	v_add_u32_e32 v6, 1, v5
	v_mad_u64_u32 v[4:5], s[4:5], v4, v3, v[4:5]
	v_cmp_ne_u32_e32 vcc, v6, v4
	v_mad_u32_u24 v3, v3, v2, 1
	s_cbranch_vccnz .Lxb_nl_0
	buffer_wbl2 sc1
	s_waitcnt vmcnt(0)
	v_mov_b32_e32 v6, s2
	v_mov_b32_e32 v7, s3
	v_add_co_u32_e32 v6, vcc, 0x2400, v6
	s_nop 1
	v_addc_co_u32_e32 v7, vcc, 0, v7, vcc
	flat_atomic_add v[6:7], v207
	flat_atomic_add v[6:7], v207 offset:256
	flat_atomic_add v[6:7], v207 offset:512
	flat_atomic_add v[6:7], v207 offset:768
	flat_atomic_add v[6:7], v207 offset:1024
	flat_atomic_add v[6:7], v207 offset:1280
	flat_atomic_add v[6:7], v207 offset:1536
	flat_atomic_add v[6:7], v207 offset:1792
	flat_atomic_add v[6:7], v207 offset:2048
	flat_atomic_add v[6:7], v207 offset:2304
	flat_atomic_add v[6:7], v207 offset:2560
	flat_atomic_add v[6:7], v207 offset:2816
	flat_atomic_add v[6:7], v207 offset:3072
	flat_atomic_add v[6:7], v207 offset:3328
	flat_atomic_add v[6:7], v207 offset:3584
	flat_atomic_add v[6:7], v207 offset:3840
	s_mov_b64 vcc, exec

.LBB0_1364:
	v_readlane_b32 s4, v251, 23
	v_readlane_b32 s5, v251, 24
	s_lshl_b64 s[4:5], s[4:5], 2
	s_add_u32 s36, s2, s4
	s_addc_u32 s28, s3, s5
	v_mov_b32_e32 v3, s36
	v_add_co_u32_e32 v6, vcc, 0x1000, v3
	v_mov_b32_e32 v3, s28
	s_nop 0
	v_addc_co_u32_e32 v7, vcc, 0, v3, vcc
	buffer_inv sc1
	flat_atomic_add v5, v[6:7], v207 offset:1024 sc0
	v_cvt_f32_u32_e32 v3, v4
	v_sub_u32_e32 v6, 0, v4
	v_rcp_iflag_f32_e32 v3, v3
	s_nop 0
	v_mul_f32_e32 v3, 0x4f7ffffe, v3
	v_cvt_u32_f32_e32 v3, v3
	v_mul_lo_u32 v6, v6, v3
	v_mul_hi_u32 v6, v3, v6
	v_add_u32_e32 v3, v3, v6
	s_waitcnt vmcnt(0) lgkmcnt(0)
	v_mul_hi_u32 v3, v5, v3
	v_mul_lo_u32 v6, v3, v4
	v_sub_u32_e32 v6, v5, v6
	v_cmp_ge_u32_e32 vcc, v6, v4
	v_add_u32_e32 v7, 1, v3
	s_nop 0
	v_cndmask_b32_e32 v3, v3, v7, vcc
	v_sub_u32_e32 v7, v6, v4
	v_cndmask_b32_e32 v6, v6, v7, vcc
	v_cmp_ge_u32_e32 vcc, v6, v4
	v_add_u32_e32 v6, 1, v3
	s_nop 0
	v_cndmask_b32_e32 v3, v3, v6, vcc
	v_add_u32_e32 v6, 1, v5
	v_mad_u64_u32 v[4:5], s[4:5], v4, v3, v[4:5]
	v_cmp_ne_u32_e32 vcc, v6, v4
	v_mad_u32_u24 v3, v3, v2, 1
	s_cbranch_vccnz .Lxb_nl_3
	buffer_wbl2 sc1
	s_waitcnt vmcnt(0)
	v_mov_b32_e32 v6, s2
	v_mov_b32_e32 v7, s3
	v_add_co_u32_e32 v6, vcc, 0x2400, v6
	s_nop 1
	v_addc_co_u32_e32 v7, vcc, 0, v7, vcc
	flat_atomic_add v[6:7], v207
	flat_atomic_add v[6:7], v207 offset:256
	flat_atomic_add v[6:7], v207 offset:512
	flat_atomic_add v[6:7], v207 offset:768
	flat_atomic_add v[6:7], v207 offset:1024
	flat_atomic_add v[6:7], v207 offset:1280
	flat_atomic_add v[6:7], v207 offset:1536
	flat_atomic_add v[6:7], v207 offset:1792
	flat_atomic_add v[6:7], v207 offset:2048
	flat_atomic_add v[6:7], v207 offset:2304
	flat_atomic_add v[6:7], v207 offset:2560
	flat_atomic_add v[6:7], v207 offset:2816
	flat_atomic_add v[6:7], v207 offset:3072
	flat_atomic_add v[6:7], v207 offset:3328
	flat_atomic_add v[6:7], v207 offset:3584
	flat_atomic_add v[6:7], v207 offset:3840
	s_mov_b64 vcc, exec

.LBB0_1795:
	v_readlane_b32 s4, v251, 23
	v_readlane_b32 s5, v251, 24
	s_lshl_b64 s[4:5], s[4:5], 2
	s_add_u32 s28, s2, s4
	s_addc_u32 s25, s3, s5
	v_mov_b32_e32 v3, s28
	v_add_co_u32_e32 v6, vcc, 0x1000, v3
	v_mov_b32_e32 v3, s25
	s_nop 0
	v_addc_co_u32_e32 v7, vcc, 0, v3, vcc
	buffer_inv sc1
	flat_atomic_add v5, v[6:7], v207 offset:1024 sc0
	v_cvt_f32_u32_e32 v3, v4
	v_sub_u32_e32 v6, 0, v4
	v_rcp_iflag_f32_e32 v3, v3
	s_nop 0
	v_mul_f32_e32 v3, 0x4f7ffffe, v3
	v_cvt_u32_f32_e32 v3, v3
	v_mul_lo_u32 v6, v6, v3
	v_mul_hi_u32 v6, v3, v6
	v_add_u32_e32 v3, v3, v6
	s_waitcnt vmcnt(0) lgkmcnt(0)
	v_mul_hi_u32 v3, v5, v3
	v_mul_lo_u32 v6, v3, v4
	v_sub_u32_e32 v6, v5, v6
	v_cmp_ge_u32_e32 vcc, v6, v4
	v_add_u32_e32 v7, 1, v3
	s_nop 0
	v_cndmask_b32_e32 v3, v3, v7, vcc
	v_sub_u32_e32 v7, v6, v4
	v_cndmask_b32_e32 v6, v6, v7, vcc
	v_cmp_ge_u32_e32 vcc, v6, v4
	v_add_u32_e32 v6, 1, v3
	s_nop 0
	v_cndmask_b32_e32 v3, v3, v6, vcc
	v_add_u32_e32 v6, 1, v5
	v_mad_u64_u32 v[4:5], s[4:5], v4, v3, v[4:5]
	v_cmp_ne_u32_e32 vcc, v6, v4
	v_mad_u32_u24 v3, v3, v2, 1
	s_cbranch_vccnz .Lxb_nl_8
	buffer_wbl2 sc1
	s_waitcnt vmcnt(0)
	v_mov_b32_e32 v6, s2
	v_mov_b32_e32 v7, s3
	v_add_co_u32_e32 v6, vcc, 0x2400, v6
	s_nop 1
	v_addc_co_u32_e32 v7, vcc, 0, v7, vcc
	flat_atomic_add v[6:7], v207
	flat_atomic_add v[6:7], v207 offset:256
	flat_atomic_add v[6:7], v207 offset:512
	flat_atomic_add v[6:7], v207 offset:768
	flat_atomic_add v[6:7], v207 offset:1024
	flat_atomic_add v[6:7], v207 offset:1280
	flat_atomic_add v[6:7], v207 offset:1536
	flat_atomic_add v[6:7], v207 offset:1792
	flat_atomic_add v[6:7], v207 offset:2048
	flat_atomic_add v[6:7], v207 offset:2304
	flat_atomic_add v[6:7], v207 offset:2560
	flat_atomic_add v[6:7], v207 offset:2816
	flat_atomic_add v[6:7], v207 offset:3072
	flat_atomic_add v[6:7], v207 offset:3328
	flat_atomic_add v[6:7], v207 offset:3584
	flat_atomic_add v[6:7], v207 offset:3840
	s_mov_b64 vcc, exec
